# LDS-DMA in the attention loop switched to SGPR-base plus 32-bit lane offset addressing (no 64-bit VALU address adds)
# speedup vs baseline: 1.0109x; 1.0109x over previous
; __device__ __forceinline__ void attn_unit(const Ctx& C, const bf16* Zqkv, const bf16* Kp, const bf16* Vp, const bf16* Zbg, bf16* Bp, const float* sg, float lam, float omli, int h, int qrow0, int seqlen, const unsigned* knmax) {
;     ...
;     int s0 = 0, s1 = 1, s2 = 2;
;     f32x16 o[4];
; #pragma unroll
;     for (int db = 0; db < 4; ++db) o[db] = f32x16{};
;     const f32x16 zero16 = f32x16{};
;     float mhat = 0.f, lsum = 0.f; bool shifted = false;
.LBB0_419:
	v_mov_b32_e32 v14, v1
	v_mov_b32_e32 v15, v1
	v_mov_b32_e32 v0, v1
	v_mov_b32_e32 v2, v1
	v_mov_b32_e32 v3, v1
	v_mov_b32_e32 v4, v1
	v_mov_b32_e32 v5, v1
	v_mov_b32_e32 v6, v1
	v_mov_b32_e32 v7, v1
	v_mov_b32_e32 v8, v1
	v_mov_b32_e32 v9, v1
	v_mov_b32_e32 v10, v1
	v_mov_b32_e32 v11, v1
	v_mov_b32_e32 v12, v1
	v_mov_b32_e32 v13, v1
	s_cmp_lg_u64 s[6:7], 0
	v_mov_b64_e32 v[30:31], v[14:15]
	v_mov_b64_e32 v[46:47], v[14:15]
	v_mov_b64_e32 v[62:63], v[14:15]
	v_mov_b64_e32 v[78:79], v[14:15]
	s_mov_b32 s54, 0
	v_mov_b32_e32 v236, 0
	s_mov_b32 s47, 2
	s_mov_b32 s46, 1
	s_mov_b32 s45, 4
	s_cselect_b64 s[0:1], -1, 0
	v_mov_b64_e32 v[28:29], v[12:13]
	v_mov_b64_e32 v[26:27], v[10:11]
	v_mov_b64_e32 v[24:25], v[8:9]
	v_mov_b64_e32 v[22:23], v[6:7]
	v_mov_b64_e32 v[20:21], v[4:5]
	v_mov_b64_e32 v[18:19], v[2:3]
	v_mov_b64_e32 v[16:17], v[0:1]
	v_mov_b64_e32 v[44:45], v[12:13]
	v_mov_b64_e32 v[42:43], v[10:11]
	v_mov_b64_e32 v[40:41], v[8:9]
	v_mov_b64_e32 v[38:39], v[6:7]
	v_mov_b64_e32 v[36:37], v[4:5]
	v_mov_b64_e32 v[34:35], v[2:3]
	v_mov_b64_e32 v[32:33], v[0:1]
	v_mov_b64_e32 v[60:61], v[12:13]
	v_mov_b64_e32 v[58:59], v[10:11]
	v_mov_b64_e32 v[56:57], v[8:9]
	v_mov_b64_e32 v[54:55], v[6:7]
	v_mov_b64_e32 v[52:53], v[4:5]
	v_mov_b64_e32 v[50:51], v[2:3]
	v_mov_b64_e32 v[48:49], v[0:1]
	v_mov_b64_e32 v[76:77], v[12:13]
	v_mov_b64_e32 v[74:75], v[10:11]
	v_mov_b64_e32 v[72:73], v[8:9]
	v_mov_b64_e32 v[70:71], v[6:7]
	v_mov_b64_e32 v[68:69], v[4:5]
	v_mov_b64_e32 v[66:67], v[2:3]
	v_mov_b64_e32 v[64:65], v[0:1]
	s_mov_b32 s49, m0
	v_readfirstlane_b32 s98, v188
	v_readfirstlane_b32 s99, v189
	v_readfirstlane_b32 s100, v190
	v_readfirstlane_b32 s101, v191
	v_lshlrev_b32_e32 v237, 4, v201
	s_nop 3
	s_mov_b32 s45, 0
	s_mov_b32 s46, 0
	s_mov_b32 s47, 1
	s_mov_b32 s54, 2
	v_exp_f32_e32 v96, v96
	v_exp_f32_e32 v97, v97
	v_exp_f32_e32 v98, v98
	v_exp_f32_e32 v99, v99
	v_exp_f32_e32 v100, v100
	v_exp_f32_e32 v101, v101
	v_exp_f32_e32 v102, v102
	v_exp_f32_e32 v103, v103
	v_add_f32_e32 v0, v96, v97
	v_add_f32_e32 v14, v98, v99
	v_add_f32_e32 v15, v0, v14
	v_cvt_pk_bf16_f32 v112, v96, v97
	v_cvt_pk_bf16_f32 v113, v98, v99
	v_exp_f32_e32 v104, v104
	v_exp_f32_e32 v105, v105
	v_exp_f32_e32 v106, v106
	v_exp_f32_e32 v107, v107
	v_add_f32_e32 v0, v100, v101
	v_add_f32_e32 v14, v102, v103
	v_add_f32_e32 v0, v0, v14
	v_add_f32_e32 v15, v15, v0
	v_cvt_pk_bf16_f32 v114, v100, v101
	v_cvt_pk_bf16_f32 v115, v102, v103
	v_exp_f32_e32 v108, v108
	v_exp_f32_e32 v109, v109
	v_exp_f32_e32 v110, v110
	v_exp_f32_e32 v111, v111
	v_add_f32_e32 v0, v104, v105
	v_add_f32_e32 v14, v106, v107
	v_add_f32_e32 v0, v0, v14
	v_add_f32_e32 v15, v15, v0
	v_cvt_pk_bf16_f32 v116, v104, v105
	v_cvt_pk_bf16_f32 v117, v106, v107
	v_exp_f32_e32 v80, v80
	v_exp_f32_e32 v81, v81
	v_exp_f32_e32 v82, v82
	v_exp_f32_e32 v83, v83
	v_add_f32_e32 v0, v108, v109
	v_add_f32_e32 v14, v110, v111
	v_add_f32_e32 v0, v0, v14
	v_add_f32_e32 v15, v15, v0
	v_cvt_pk_bf16_f32 v118, v108, v109
	v_cvt_pk_bf16_f32 v119, v110, v111
	v_exp_f32_e32 v84, v84
	v_exp_f32_e32 v85, v85
	v_exp_f32_e32 v86, v86
	v_exp_f32_e32 v87, v87
	v_add_f32_e32 v0, v80, v81
	v_add_f32_e32 v14, v82, v83
	v_add_f32_e32 v0, v0, v14
	v_add_f32_e32 v15, v15, v0
	v_cvt_pk_bf16_f32 v120, v80, v81
	v_cvt_pk_bf16_f32 v121, v82, v83
	v_exp_f32_e32 v88, v88
	v_exp_f32_e32 v89, v89
	v_exp_f32_e32 v90, v90
	v_exp_f32_e32 v91, v91
	v_add_f32_e32 v0, v84, v85
	v_add_f32_e32 v14, v86, v87
	v_add_f32_e32 v0, v0, v14
	v_add_f32_e32 v15, v15, v0
	v_cvt_pk_bf16_f32 v122, v84, v85
	v_cvt_pk_bf16_f32 v123, v86, v87
	v_exp_f32_e32 v92, v92
	v_exp_f32_e32 v93, v93
	v_exp_f32_e32 v94, v94
	v_exp_f32_e32 v95, v95
	v_add_f32_e32 v0, v88, v89
	v_add_f32_e32 v14, v90, v91
	v_add_f32_e32 v0, v0, v14
	v_add_f32_e32 v15, v15, v0
	v_cvt_pk_bf16_f32 v124, v88, v89
	v_cvt_pk_bf16_f32 v125, v90, v91
	v_add_f32_e32 v0, v92, v93
	v_add_f32_e32 v14, v94, v95
	v_add_f32_e32 v0, v0, v14
	v_add_f32_e32 v15, v15, v0
	v_cvt_pk_bf16_f32 v126, v92, v93
	v_cvt_pk_bf16_f32 v127, v94, v95
	v_add_f32_e32 v236, v236, v15
	s_lshl_b32 s55, s47, 14
	v_add_u32_e32 v12, s55, v175
	ds_read_b128 v[128:131], v12
	ds_read_b128 v[132:135], v12 offset:512
	ds_read_b128 v[136:139], v12 offset:2048
	ds_read_b128 v[140:143], v12 offset:2560
	s_lshl_b32 s56, s46, 14
	v_add_u32_e32 v13, s56, v204
	s_add_i32 s6, s45, 3
	s_min_u32 s6, s6, s13
	s_lshl_b32 s6, s6, 13
	s_add_u32 s64, s98, s6
	s_addc_u32 s65, s99, 0
	s_add_i32 s6, s45, 2
	s_min_u32 s6, s6, s13
	s_lshl_b32 s6, s6, 14
	s_add_u32 s6, s100, s6
	s_addc_u32 s7, s101, 0
	s_add_i32 s51, s56, s37
	s_lshl_b32 s57, s54, 14
	s_add_i32 s57, s57, s38
	s_waitcnt vmcnt(0)
	s_and_b64 vcc, exec, s[8:9]
	s_cbranch_vccz .Latt_loop
	s_barrier
.Latt_loop:
	s_setprio 1
	s_waitcnt lgkmcnt(3)
	v_mfma_f32_32x32x16_bf16 v[96:111], v[128:131], v[144:147], 0
	ds_read_b128 v[128:131], v12 offset:4096
	s_waitcnt lgkmcnt(3)
	v_mfma_f32_32x32x16_bf16 v[80:95], v[132:135], v[144:147], 0
	ds_read_b128 v[132:135], v12 offset:4608
	s_mov_b32 m0, s51
	s_nop 0
	global_load_lds_dwordx4 v237, s[64:65]
	s_add_u32 s64, s64, 0x200000
	s_addc_u32 s65, s65, 0
	s_waitcnt lgkmcnt(3)
	v_mfma_f32_32x32x16_bf16 v[96:111], v[136:139], v[148:151], v[96:111]
	ds_read_b128 v[136:139], v12 offset:6144
	s_waitcnt lgkmcnt(3)
	v_mfma_f32_32x32x16_bf16 v[80:95], v[140:143], v[148:151], v[80:95]
	ds_read_b128 v[140:143], v12 offset:6656
	s_add_i32 m0, s51, 0x2000
	s_nop 0
	global_load_lds_dwordx4 v237, s[64:65]
	s_waitcnt lgkmcnt(3)
	v_mfma_f32_32x32x16_bf16 v[96:111], v[128:131], v[152:155], v[96:111]
	ds_read_b128 v[238:241], v13 offset:49152
	s_waitcnt lgkmcnt(3)
	v_mfma_f32_32x32x16_bf16 v[80:95], v[132:135], v[152:155], v[80:95]
	ds_read_b128 v[242:245], v13 offset:53248
	s_mov_b32 m0, s57
	s_nop 0
	global_load_lds_dwordx4 v237, s[6:7]
	s_add_u32 s6, s6, 0x2000
	s_addc_u32 s7, s7, 0
	s_waitcnt lgkmcnt(3)
	v_mfma_f32_32x32x16_bf16 v[96:111], v[136:139], v[156:159], v[96:111]
	ds_read_b128 v[246:249], v13 offset:57344
	s_waitcnt lgkmcnt(3)
	v_mfma_f32_32x32x16_bf16 v[80:95], v[140:143], v[156:159], v[80:95]
	ds_read_b128 v[250:253], v13 offset:61440
	s_add_i32 m0, s57, 0x2000
	s_nop 0
	global_load_lds_dwordx4 v237, s[6:7]
	s_waitcnt lgkmcnt(3)
	v_mfma_f32_32x32x16_bf16 v[64:79], v[112:115], v[238:241], v[64:79]
	ds_read_b128 v[238:241], v13 offset:50176
	s_waitcnt lgkmcnt(3)
	v_mfma_f32_32x32x16_bf16 v[48:63], v[112:115], v[242:245], v[48:63]
	ds_read_b128 v[242:245], v13 offset:54272
	s_waitcnt lgkmcnt(3)
	v_mfma_f32_32x32x16_bf16 v[32:47], v[112:115], v[246:249], v[32:47]
	ds_read_b128 v[246:249], v13 offset:58368
	s_waitcnt lgkmcnt(3)
	v_mfma_f32_32x32x16_bf16 v[16:31], v[112:115], v[250:253], v[16:31]
	ds_read_b128 v[250:253], v13 offset:62464
	s_waitcnt lgkmcnt(3)
	v_mfma_f32_32x32x16_bf16 v[64:79], v[116:119], v[238:241], v[64:79]
	ds_read_b128 v[238:241], v13 offset:51200
	s_waitcnt lgkmcnt(3)
	v_mfma_f32_32x32x16_bf16 v[48:63], v[116:119], v[242:245], v[48:63]
	ds_read_b128 v[242:245], v13 offset:55296
	s_waitcnt lgkmcnt(3)
	v_mfma_f32_32x32x16_bf16 v[32:47], v[116:119], v[246:249], v[32:47]
	ds_read_b128 v[246:249], v13 offset:59392
	s_waitcnt lgkmcnt(3)
	v_mfma_f32_32x32x16_bf16 v[16:31], v[116:119], v[250:253], v[16:31]
	ds_read_b128 v[250:253], v13 offset:63488
	s_waitcnt lgkmcnt(3)
	v_mfma_f32_32x32x16_bf16 v[64:79], v[120:123], v[238:241], v[64:79]
	ds_read_b128 v[238:241], v13 offset:52224
	s_waitcnt lgkmcnt(3)
	v_mfma_f32_32x32x16_bf16 v[48:63], v[120:123], v[242:245], v[48:63]
	ds_read_b128 v[242:245], v13 offset:56320
	s_waitcnt lgkmcnt(3)
	v_mfma_f32_32x32x16_bf16 v[32:47], v[120:123], v[246:249], v[32:47]
	ds_read_b128 v[246:249], v13 offset:60416
	s_waitcnt lgkmcnt(3)
	v_mfma_f32_32x32x16_bf16 v[16:31], v[120:123], v[250:253], v[16:31]
	ds_read_b128 v[250:253], v13 offset:64512
	s_waitcnt lgkmcnt(3)
	v_mfma_f32_32x32x16_bf16 v[64:79], v[124:127], v[238:241], v[64:79]
	s_waitcnt lgkmcnt(2)
	v_mfma_f32_32x32x16_bf16 v[48:63], v[124:127], v[242:245], v[48:63]
	s_waitcnt lgkmcnt(1)
	v_mfma_f32_32x32x16_bf16 v[32:47], v[124:127], v[246:249], v[32:47]
	s_waitcnt lgkmcnt(0)
	v_mfma_f32_32x32x16_bf16 v[16:31], v[124:127], v[250:253], v[16:31]
	s_barrier
	s_setprio 0
	s_add_i32 s45, s45, 1
	s_mov_b32 s6, s46
	s_mov_b32 s46, s47
	s_mov_b32 s47, s54
	s_mov_b32 s54, s6
	s_cmp_ge_u32 s45, s11
	s_cbranch_scc1 .Latt_last
	s_andn2_b64 vcc, exec, s[0:1]
	s_cbranch_vccnz .Latt_exp
	v_max3_f32 v0, v96, v97, v98
	v_max3_f32 v2, v80, v81, v82
	s_andn2_b64 vcc, exec, s[2:3]
	v_max3_f32 v0, v0, v99, v100
	v_max3_f32 v2, v2, v83, v84
	s_nop 0
	v_max3_f32 v0, v0, v101, v102
	v_max3_f32 v2, v2, v85, v86
	s_nop 0
	v_max3_f32 v0, v0, v103, v104
	v_max3_f32 v2, v2, v87, v88
	s_nop 0
	v_max3_f32 v0, v0, v105, v106
	v_max3_f32 v2, v2, v89, v90
	s_nop 0
	v_max3_f32 v0, v0, v107, v108
	v_max3_f32 v2, v2, v91, v92
	s_nop 0
	v_max3_f32 v0, v0, v109, v110
	v_max3_f32 v2, v2, v93, v94
	s_nop 0
	v_max3_f32 v0, v0, v111, v95
	s_nop 0
	v_max_f32_e32 v0, v0, v2
	s_nop 0
	v_mov_b32_e32 v2, v0
	s_nop 1
	v_permlane32_swap_b32_e32 v0, v2
	v_max_f32_e32 v0, v0, v2
	s_cbranch_vccnz .Latt_x1
	v_sub_f32_e32 v111, v111, v235
	v_sub_f32_e32 v110, v110, v235
	v_sub_f32_e32 v109, v109, v235
	v_sub_f32_e32 v108, v108, v235
	v_sub_f32_e32 v107, v107, v235
	v_sub_f32_e32 v106, v106, v235
	v_sub_f32_e32 v105, v105, v235
	v_sub_f32_e32 v104, v104, v235
	v_sub_f32_e32 v103, v103, v235
	v_sub_f32_e32 v102, v102, v235
	v_sub_f32_e32 v101, v101, v235
	v_sub_f32_e32 v100, v100, v235
	v_sub_f32_e32 v99, v99, v235
	v_sub_f32_e32 v98, v98, v235
	v_sub_f32_e32 v97, v97, v235
	v_sub_f32_e32 v96, v96, v235
	v_sub_f32_e32 v95, v95, v235
	v_sub_f32_e32 v94, v94, v235
	v_sub_f32_e32 v93, v93, v235
	v_sub_f32_e32 v92, v92, v235
	v_sub_f32_e32 v91, v91, v235
	v_sub_f32_e32 v90, v90, v235
	v_sub_f32_e32 v89, v89, v235
	v_sub_f32_e32 v88, v88, v235
	v_sub_f32_e32 v87, v87, v235
	v_sub_f32_e32 v86, v86, v235
	v_sub_f32_e32 v85, v85, v235
	v_sub_f32_e32 v84, v84, v235
	v_sub_f32_e32 v83, v83, v235
	v_sub_f32_e32 v82, v82, v235
	v_sub_f32_e32 v81, v81, v235
	v_sub_f32_e32 v80, v80, v235

.Latt_exp:
	v_exp_f32_e32 v96, v96
	v_exp_f32_e32 v97, v97
	v_exp_f32_e32 v98, v98
	v_exp_f32_e32 v99, v99
	v_exp_f32_e32 v100, v100
	v_exp_f32_e32 v101, v101
	v_exp_f32_e32 v102, v102
	v_exp_f32_e32 v103, v103
	v_add_f32_e32 v0, v96, v97
	v_add_f32_e32 v14, v98, v99
	v_add_f32_e32 v15, v0, v14
	v_cvt_pk_bf16_f32 v112, v96, v97
	v_cvt_pk_bf16_f32 v113, v98, v99
	v_exp_f32_e32 v104, v104
	v_exp_f32_e32 v105, v105
	v_exp_f32_e32 v106, v106
	v_exp_f32_e32 v107, v107
	v_add_f32_e32 v0, v100, v101
	v_add_f32_e32 v14, v102, v103
	v_add_f32_e32 v0, v0, v14
	v_add_f32_e32 v15, v15, v0
	v_cvt_pk_bf16_f32 v114, v100, v101
	v_cvt_pk_bf16_f32 v115, v102, v103
	v_exp_f32_e32 v108, v108
	v_exp_f32_e32 v109, v109
	v_exp_f32_e32 v110, v110
	v_exp_f32_e32 v111, v111
	v_add_f32_e32 v0, v104, v105
	v_add_f32_e32 v14, v106, v107
	v_add_f32_e32 v0, v0, v14
	v_add_f32_e32 v15, v15, v0
	v_cvt_pk_bf16_f32 v116, v104, v105
	v_cvt_pk_bf16_f32 v117, v106, v107
	v_exp_f32_e32 v80, v80
	v_exp_f32_e32 v81, v81
	v_exp_f32_e32 v82, v82
	v_exp_f32_e32 v83, v83
	v_add_f32_e32 v0, v108, v109
	v_add_f32_e32 v14, v110, v111
	v_add_f32_e32 v0, v0, v14
	v_add_f32_e32 v15, v15, v0
	v_cvt_pk_bf16_f32 v118, v108, v109
	v_cvt_pk_bf16_f32 v119, v110, v111
	v_exp_f32_e32 v84, v84
	v_exp_f32_e32 v85, v85
	v_exp_f32_e32 v86, v86
	v_exp_f32_e32 v87, v87
	v_add_f32_e32 v0, v80, v81
	v_add_f32_e32 v14, v82, v83
	v_add_f32_e32 v0, v0, v14
	v_add_f32_e32 v15, v15, v0
	v_cvt_pk_bf16_f32 v120, v80, v81
	v_cvt_pk_bf16_f32 v121, v82, v83
	v_exp_f32_e32 v88, v88
	v_exp_f32_e32 v89, v89
	v_exp_f32_e32 v90, v90
	v_exp_f32_e32 v91, v91
	v_add_f32_e32 v0, v84, v85
	v_add_f32_e32 v14, v86, v87
	v_add_f32_e32 v0, v0, v14
	v_add_f32_e32 v15, v15, v0
	v_cvt_pk_bf16_f32 v122, v84, v85
	v_cvt_pk_bf16_f32 v123, v86, v87
	v_exp_f32_e32 v92, v92
	v_exp_f32_e32 v93, v93
	v_exp_f32_e32 v94, v94
	v_exp_f32_e32 v95, v95
	v_add_f32_e32 v0, v88, v89
	v_add_f32_e32 v14, v90, v91
	v_add_f32_e32 v0, v0, v14
	v_add_f32_e32 v15, v15, v0
	v_cvt_pk_bf16_f32 v124, v88, v89
	v_cvt_pk_bf16_f32 v125, v90, v91
	v_add_f32_e32 v0, v92, v93
	v_add_f32_e32 v14, v94, v95
	v_add_f32_e32 v0, v0, v14
	v_add_f32_e32 v15, v15, v0
	v_cvt_pk_bf16_f32 v126, v92, v93
	v_cvt_pk_bf16_f32 v127, v94, v95
	v_add_f32_e32 v236, v236, v15
	s_lshl_b32 s55, s47, 14
	v_add_u32_e32 v12, s55, v175
	ds_read_b128 v[128:131], v12
	ds_read_b128 v[132:135], v12 offset:512
	ds_read_b128 v[136:139], v12 offset:2048
	ds_read_b128 v[140:143], v12 offset:2560
	s_lshl_b32 s56, s46, 14
	v_add_u32_e32 v13, s56, v204
	s_add_i32 s6, s45, 3
	s_min_u32 s6, s6, s13
	s_lshl_b32 s6, s6, 13
	s_add_u32 s64, s98, s6
	s_addc_u32 s65, s99, 0
	s_add_i32 s6, s45, 2
	s_min_u32 s6, s6, s13
	s_lshl_b32 s6, s6, 14
	s_add_u32 s6, s100, s6
	s_addc_u32 s7, s101, 0
	s_add_i32 s51, s56, s37
	s_lshl_b32 s57, s54, 14
	s_add_i32 s57, s57, s38
	s_waitcnt vmcnt(0)
	s_barrier
	s_branch .Latt_loop

; #define LAS __attribute__((address_space(3)))
; __global__ void __launch_bounds__(NTHREADS, 2) fwd_kernel(Params p) {
;     extern __shared__ __attribute__((aligned(16))) unsigned char lds_raw[];
;     { const int t0 = threadIdx.x; if (t0 == 0) { LAS double* tab = (LAS double*)((LAS unsigned char*)lds_raw + LDS_TAB);
; #pragma unroll
;         for (int i = 0; i < 32; ++i) tab[i] = p.invrev[i]; } }
;     if (blockIdx.x == 0) { unsigned* bw = (unsigned*)(p.ws + WS_BAR); for (int i = threadIdx.x; i < XCD_BAR_WORDS; i += NTHREADS) bw[i] = 0u; }
;     if (blockIdx.x == 0 && threadIdx.x < 384) ((unsigned*)(p.ws + WS_PCNT))[threadIdx.x] = 0u;
;     if (threadIdx.x < 2) ((volatile LAS unsigned*)((LAS unsigned char*)lds_raw + LDS_ST))[threadIdx.x] = 0u;
;     __syncthreads();
;     XcdBarrier bar; bar.bar = (unsigned*)(p.ws + WS_BAR); bar.x = 0; bar.st = (volatile LAS unsigned*)((LAS unsigned char*)lds_raw + LDS_ST);
	.amdhsa_kernel _Z10fwd_kernel6Params
		.amdhsa_group_segment_fixed_size 0
		.amdhsa_private_segment_fixed_size 0
		.amdhsa_kernarg_size 696
		.amdhsa_user_sgpr_count 2
		.amdhsa_user_sgpr_dispatch_ptr 0
		.amdhsa_user_sgpr_queue_ptr 0
		.amdhsa_user_sgpr_kernarg_segment_ptr 1
		.amdhsa_user_sgpr_dispatch_id 0
		.amdhsa_user_sgpr_kernarg_preload_length 0
		.amdhsa_user_sgpr_kernarg_preload_offset 0
		.amdhsa_user_sgpr_private_segment_size 0
		.amdhsa_uses_dynamic_stack 0
		.amdhsa_enable_private_segment 0
		.amdhsa_system_sgpr_workgroup_id_x 1
		.amdhsa_system_sgpr_workgroup_id_y 0
		.amdhsa_system_sgpr_workgroup_id_z 0
		.amdhsa_system_sgpr_workgroup_info 0
		.amdhsa_system_vgpr_workitem_id 2
		.amdhsa_next_free_vgpr 256
		.amdhsa_next_free_sgpr 102
		.amdhsa_accum_offset 256
		.amdhsa_reserve_vcc 1
		.amdhsa_float_round_mode_32 0
		.amdhsa_float_round_mode_16_64 0
		.amdhsa_float_denorm_mode_32 3
		.amdhsa_float_denorm_mode_16_64 3
		.amdhsa_dx10_clamp 1
		.amdhsa_ieee_mode 1
		.amdhsa_fp16_overflow 0
		.amdhsa_tg_split 0
		.amdhsa_exception_fp_ieee_invalid_op 0
		.amdhsa_exception_fp_denorm_src 0
		.amdhsa_exception_fp_ieee_div_zero 0
		.amdhsa_exception_fp_ieee_overflow 0
		.amdhsa_exception_fp_ieee_underflow 0
		.amdhsa_exception_fp_ieee_inexact 0
		.amdhsa_exception_int_div_zero 0
	.end_amdhsa_kernel
